# band path v2: near-tile relative-position bias pre-loaded into the score accumulator (MFMA C operand) during the previous step, DMA issue moved from the step top into an MFMA gap
# speedup vs baseline: 1.0493x; 1.0011x over previous
.Lbd_w_7:
	s_waitcnt lgkmcnt(0)
	s_barrier
	s_add_i32 s10, s79, 0
	s_and_b32 s10, s10, 3
	s_lshl_b32 s10, s10, 13
	v_add_u32_e32 v2, s10, v241
	v_mfma_f32_32x32x16_bf16 v[162:177], v[194:197], v[146:149], v[66:81]
	v_exp_f32_e32 v114, v114
	v_exp_f32_e32 v115, v115
	v_exp_f32_e32 v116, v116
	v_add_f32_e32 v22, v114, v115
	v_exp_f32_e32 v117, v117
	ds_read_b64_tr_b16 v[98:99], v2 offset:49152
	ds_read_b64_tr_b16 v[100:101], v2 offset:49664
	ds_read_b64_tr_b16 v[102:103], v2 offset:50176
	ds_read_b64_tr_b16 v[104:105], v2 offset:50688
	v_mfma_f32_32x32x16_bf16 v[178:193], v[198:201], v[146:149], v[66:81]
	v_exp_f32_e32 v118, v118
	v_add_f32_e32 v22, v22, v116
	v_exp_f32_e32 v119, v119
	v_add_f32_e32 v22, v22, v117
	v_exp_f32_e32 v120, v120
	ds_read_b64_tr_b16 v[106:107], v2 offset:51200
	ds_read_b64_tr_b16 v[108:109], v2 offset:51712
	ds_read_b64_tr_b16 v[110:111], v2 offset:52224
	ds_read_b64_tr_b16 v[112:113], v2 offset:52736
	v_mfma_f32_32x32x16_bf16 v[162:177], v[202:205], v[150:153], v[162:177]
	v_add_f32_e32 v22, v22, v118
	v_exp_f32_e32 v121, v121
	v_add_f32_e32 v22, v22, v119
	v_add_f32_e32 v22, v22, v120
	v_add_f32_e32 v22, v22, v121
	ds_read_b64_tr_b16 v[4:5], v2 offset:53248
	ds_read_b64_tr_b16 v[6:7], v2 offset:53760
	ds_read_b64_tr_b16 v[8:9], v2 offset:54272
	ds_read_b64_tr_b16 v[10:11], v2 offset:54784
	v_mfma_f32_32x32x16_bf16 v[178:193], v[206:209], v[150:153], v[178:193]
	v_cvt_pk_bf16_f32 v114, v114, v115
	v_cvt_pk_bf16_f32 v115, v116, v117
	v_cvt_pk_bf16_f32 v116, v118, v119
	v_cvt_pk_bf16_f32 v117, v120, v121
	ds_read_b64_tr_b16 v[12:13], v2 offset:55296
	ds_read_b64_tr_b16 v[14:15], v2 offset:55808
	ds_read_b64_tr_b16 v[16:17], v2 offset:56320
	ds_read_b64_tr_b16 v[18:19], v2 offset:56832
	v_mfma_f32_32x32x16_bf16 v[162:177], v[210:213], v[154:157], v[162:177]
	v_exp_f32_e32 v122, v122
	v_exp_f32_e32 v123, v123
	v_exp_f32_e32 v124, v124
	v_add_f32_e32 v22, v22, v122
	v_exp_f32_e32 v125, v125
	s_cmp_gt_u32 s79, 8
	s_cbranch_scc1 .Lbd_dk_9
	s_add_i32 s0, s79, 3
	s_and_b32 s0, s0, 3
	s_lshl_b32 s0, s0, 13
	s_add_u32 m0, s24, s0
	s_cmp_gt_u32 s79, 7
	global_load_lds_dwordx4 v[26:27], off
	v_lshl_add_u64 v[26:27], v[26:27], 0, s[30:31]
	s_cbranch_scc1 .Lbd_dk_9
	s_and_b32 s0, s79, 3
	s_mulk_i32 s0, 0x3000
	s_add_u32 m0, s71, s0
	s_nop 0
	global_load_lds_dwordx4 v[24:25], off
	v_lshl_add_u64 v[24:25], v[24:25], 0, s[30:31]
.Lbd_dk_9:
	v_mfma_f32_32x32x16_bf16 v[178:193], v[214:217], v[154:157], v[178:193]
	v_add_f32_e32 v22, v22, v123
	v_exp_f32_e32 v126, v126
	v_add_f32_e32 v22, v22, v124
	v_exp_f32_e32 v127, v127
	v_add_f32_e32 v22, v22, v125
	v_mfma_f32_32x32x16_bf16 v[162:177], v[218:221], v[158:161], v[162:177]
	v_exp_f32_e32 v128, v128
	v_add_f32_e32 v22, v22, v126
	v_exp_f32_e32 v129, v129
	v_add_f32_e32 v22, v22, v127
	v_add_f32_e32 v22, v22, v128
	v_mfma_f32_32x32x16_bf16 v[178:193], v[222:225], v[158:161], v[178:193]
	v_add_f32_e32 v22, v22, v129
	v_cvt_pk_bf16_f32 v122, v122, v123
	v_cvt_pk_bf16_f32 v123, v124, v125
	v_cvt_pk_bf16_f32 v124, v126, v127
	v_cvt_pk_bf16_f32 v125, v128, v129
	s_waitcnt lgkmcnt(0)
	s_add_i32 s10, s79, 2
	s_and_b32 s10, s10, 3
	s_mulk_i32 s10, 0x3000
	v_add_u32_e32 v2, s10, v239
	v_mfma_f32_32x32x16_bf16 v[50:65], v[114:117], v[98:101], v[50:65]
	v_exp_f32_e32 v130, v130
	v_exp_f32_e32 v131, v131
	v_exp_f32_e32 v132, v132
	v_add_f32_e32 v22, v22, v130
	v_exp_f32_e32 v133, v133
	v_add_f32_e32 v22, v22, v131
	v_exp_f32_e32 v134, v134
	v_add_f32_e32 v22, v22, v132
	v_exp_f32_e32 v135, v135
	v_add_f32_e32 v22, v22, v133
	ds_read_b128 v[194:197], v2
	ds_read_b128 v[198:201], v2 offset:512
	v_mfma_f32_32x32x16_bf16 v[34:49], v[114:117], v[4:7], v[34:49]
	v_exp_f32_e32 v136, v136
	v_add_f32_e32 v22, v22, v134
	v_exp_f32_e32 v137, v137
	v_add_f32_e32 v22, v22, v135
	v_add_f32_e32 v22, v22, v136
	v_add_f32_e32 v22, v22, v137
	v_cvt_pk_bf16_f32 v130, v130, v131
	v_cvt_pk_bf16_f32 v131, v132, v133
	v_cvt_pk_bf16_f32 v132, v134, v135
	v_cvt_pk_bf16_f32 v133, v136, v137
	ds_read_b128 v[202:205], v2 offset:2048
	ds_read_b128 v[206:209], v2 offset:2560
	v_mfma_f32_32x32x16_bf16 v[50:65], v[122:125], v[102:105], v[50:65]
	v_exp_f32_e32 v138, v138
	v_exp_f32_e32 v139, v139
	v_exp_f32_e32 v140, v140
	v_add_f32_e32 v22, v22, v138
	v_exp_f32_e32 v141, v141
	v_add_f32_e32 v22, v22, v139
	v_exp_f32_e32 v142, v142
	v_add_f32_e32 v22, v22, v140
	v_exp_f32_e32 v143, v143
	v_add_f32_e32 v22, v22, v141
	ds_read_b128 v[210:213], v2 offset:4096
	ds_read_b128 v[214:217], v2 offset:4608
	v_mfma_f32_32x32x16_bf16 v[34:49], v[122:125], v[8:11], v[34:49]
	v_exp_f32_e32 v144, v144
	v_add_f32_e32 v22, v22, v142
	v_exp_f32_e32 v145, v145
	v_add_f32_e32 v22, v22, v143
	v_add_f32_e32 v22, v22, v144
	v_add_f32_e32 v22, v22, v145
	v_cvt_pk_bf16_f32 v138, v138, v139
	v_cvt_pk_bf16_f32 v139, v140, v141
	v_cvt_pk_bf16_f32 v140, v142, v143
	v_cvt_pk_bf16_f32 v141, v144, v145
	v_add_f32_e32 v240, v240, v22
	ds_read_b128 v[218:221], v2 offset:6144
	ds_read_b128 v[222:225], v2 offset:6656
	v_mfma_f32_32x32x16_bf16 v[50:65], v[130:133], v[106:109], v[50:65]
	v_max3_f32 v20, v162, v163, v164
	v_max3_f32 v21, v165, v166, v167
	v_max3_f32 v20, v20, v168, v169
	v_max3_f32 v21, v21, v170, v171
	v_max3_f32 v20, v20, v172, v173
	v_mfma_f32_32x32x16_bf16 v[34:49], v[130:133], v[12:15], v[34:49]
	v_max3_f32 v21, v21, v174, v175
	v_max3_f32 v20, v20, v176, v177
	v_max3_f32 v21, v21, v178, v179
	v_max3_f32 v20, v20, v180, v181
	v_max3_f32 v21, v21, v182, v183
	v_mfma_f32_32x32x16_bf16 v[50:65], v[138:141], v[110:113], v[50:65]
	v_max3_f32 v20, v20, v184, v185
	v_max3_f32 v21, v21, v186, v187
	v_max3_f32 v20, v20, v188, v189
	v_max3_f32 v21, v21, v190, v191
	v_mfma_f32_32x32x16_bf16 v[34:49], v[138:141], v[16:19], v[34:49]
	v_max3_f32 v20, v20, v192, v193
	v_max_f32_e32 v20, v20, v21
	v_cmp_lt_f32_e32 vcc, s41, v20
	s_cbranch_vccz .Lbd_nors_10
	s_nop 15
	s_nop 15
	v_mov_b32_e32 v21, v20
	s_nop 1
	v_permlane32_swap_b32_e32 v20, v21
	v_max_f32_e32 v20, v20, v21
	v_max_f32_e32 v20, v20, v20
	v_max_f32_e32 v122, 0, v20
	v_exp_f32_e64 v123, -v122
	v_add_f32_e32 v242, v242, v122
	v_xor_b32_e32 v82, 0x80000000, v242
	v_sub_f32_e32 v66, v23, v242
	v_mov_b32_e32 v83, v82
	v_mov_b32_e32 v67, v66
	v_mov_b32_e32 v84, v82
	v_mov_b32_e32 v68, v66
	v_mov_b32_e32 v85, v82
	v_mov_b32_e32 v69, v66
	v_mov_b32_e32 v86, v82
	v_mov_b32_e32 v70, v66
	v_mov_b32_e32 v87, v82
	v_mov_b32_e32 v71, v66
	v_mov_b32_e32 v88, v82
	v_mov_b32_e32 v72, v66
	v_mov_b32_e32 v89, v82
	v_mov_b32_e32 v73, v66
	v_mov_b32_e32 v90, v82
	v_mov_b32_e32 v74, v66
	v_mov_b32_e32 v91, v82
	v_mov_b32_e32 v75, v66
	v_mov_b32_e32 v92, v82
	v_mov_b32_e32 v76, v66
	v_mov_b32_e32 v93, v82
	v_mov_b32_e32 v77, v66
	v_mov_b32_e32 v94, v82
	v_mov_b32_e32 v78, v66
	v_mov_b32_e32 v95, v82
	v_mov_b32_e32 v79, v66
	v_mov_b32_e32 v96, v82
	v_mov_b32_e32 v80, v66
	v_mov_b32_e32 v97, v82
	v_mov_b32_e32 v81, v66
	v_sub_f32_e32 v162, v162, v122
	v_sub_f32_e32 v163, v163, v122
	v_sub_f32_e32 v164, v164, v122
	v_sub_f32_e32 v165, v165, v122
	v_sub_f32_e32 v166, v166, v122
	v_sub_f32_e32 v167, v167, v122
	v_sub_f32_e32 v168, v168, v122
	v_sub_f32_e32 v169, v169, v122
	v_sub_f32_e32 v170, v170, v122
	v_sub_f32_e32 v171, v171, v122
	v_sub_f32_e32 v172, v172, v122
	v_sub_f32_e32 v173, v173, v122
	v_sub_f32_e32 v174, v174, v122
	v_sub_f32_e32 v175, v175, v122
	v_sub_f32_e32 v176, v176, v122
	v_sub_f32_e32 v177, v177, v122
	v_sub_f32_e32 v178, v178, v122
	v_sub_f32_e32 v179, v179, v122
	v_sub_f32_e32 v180, v180, v122
	v_sub_f32_e32 v181, v181, v122
	v_sub_f32_e32 v182, v182, v122
	v_sub_f32_e32 v183, v183, v122
	v_sub_f32_e32 v184, v184, v122
	v_sub_f32_e32 v185, v185, v122
	v_sub_f32_e32 v186, v186, v122
	v_sub_f32_e32 v187, v187, v122
	v_sub_f32_e32 v188, v188, v122
	v_sub_f32_e32 v189, v189, v122
	v_sub_f32_e32 v190, v190, v122
	v_sub_f32_e32 v191, v191, v122
	v_sub_f32_e32 v192, v192, v122
	v_sub_f32_e32 v193, v193, v122
	v_mul_f32_e32 v240, v240, v123
	v_cmp_gt_u32_e32 vcc, 32, v233
	s_and_saveexec_b64 s[12:13], vcc
	ds_write_b32 v244, v123
	s_mov_b64 exec, s[12:13]
	ds_read_b128 v[126:129], v237 offset:0
	s_waitcnt lgkmcnt(0)
	v_mul_f32_e32 v50, v50, v126
	v_mul_f32_e32 v34, v34, v126
	v_mul_f32_e32 v51, v51, v127
	v_mul_f32_e32 v35, v35, v127
	v_mul_f32_e32 v52, v52, v128
	v_mul_f32_e32 v36, v36, v128
	v_mul_f32_e32 v53, v53, v129
	v_mul_f32_e32 v37, v37, v129
	ds_read_b128 v[126:129], v237 offset:32
	s_waitcnt lgkmcnt(0)
	v_mul_f32_e32 v54, v54, v126
	v_mul_f32_e32 v38, v38, v126
	v_mul_f32_e32 v55, v55, v127
	v_mul_f32_e32 v39, v39, v127
	v_mul_f32_e32 v56, v56, v128
	v_mul_f32_e32 v40, v40, v128
	v_mul_f32_e32 v57, v57, v129
	v_mul_f32_e32 v41, v41, v129
	ds_read_b128 v[126:129], v237 offset:64
	s_waitcnt lgkmcnt(0)
	v_mul_f32_e32 v58, v58, v126
	v_mul_f32_e32 v42, v42, v126
	v_mul_f32_e32 v59, v59, v127
	v_mul_f32_e32 v43, v43, v127
	v_mul_f32_e32 v60, v60, v128
	v_mul_f32_e32 v44, v44, v128
	v_mul_f32_e32 v61, v61, v129
	v_mul_f32_e32 v45, v45, v129
	ds_read_b128 v[126:129], v237 offset:96
	s_waitcnt lgkmcnt(0)
	v_mul_f32_e32 v62, v62, v126
	v_mul_f32_e32 v46, v46, v126
	v_mul_f32_e32 v63, v63, v127
	v_mul_f32_e32 v47, v47, v127
	v_mul_f32_e32 v64, v64, v128
	v_mul_f32_e32 v48, v48, v128
	v_mul_f32_e32 v65, v65, v129
	v_mul_f32_e32 v49, v49, v129

.Lbd_w_11:
	s_waitcnt lgkmcnt(0)
	s_barrier
	s_add_i32 s10, s79, 0
	s_and_b32 s10, s10, 3
	s_lshl_b32 s10, s10, 13
	v_add_u32_e32 v2, s10, v241
	v_mfma_f32_32x32x16_bf16 v[114:129], v[194:197], v[146:149], v[66:81]
	v_exp_f32_e32 v162, v162
	v_exp_f32_e32 v163, v163
	v_exp_f32_e32 v164, v164
	v_add_f32_e32 v22, v162, v163
	v_exp_f32_e32 v165, v165
	ds_read_b64_tr_b16 v[98:99], v2 offset:49152
	ds_read_b64_tr_b16 v[100:101], v2 offset:49664
	ds_read_b64_tr_b16 v[102:103], v2 offset:50176
	ds_read_b64_tr_b16 v[104:105], v2 offset:50688
	v_mfma_f32_32x32x16_bf16 v[130:145], v[198:201], v[146:149], v[66:81]
	v_exp_f32_e32 v166, v166
	v_add_f32_e32 v22, v22, v164
	v_exp_f32_e32 v167, v167
	v_add_f32_e32 v22, v22, v165
	v_exp_f32_e32 v168, v168
	ds_read_b64_tr_b16 v[106:107], v2 offset:51200
	ds_read_b64_tr_b16 v[108:109], v2 offset:51712
	ds_read_b64_tr_b16 v[110:111], v2 offset:52224
	ds_read_b64_tr_b16 v[112:113], v2 offset:52736
	v_mfma_f32_32x32x16_bf16 v[114:129], v[202:205], v[150:153], v[114:129]
	v_add_f32_e32 v22, v22, v166
	v_exp_f32_e32 v169, v169
	v_add_f32_e32 v22, v22, v167
	v_add_f32_e32 v22, v22, v168
	v_add_f32_e32 v22, v22, v169
	ds_read_b64_tr_b16 v[4:5], v2 offset:53248
	ds_read_b64_tr_b16 v[6:7], v2 offset:53760
	ds_read_b64_tr_b16 v[8:9], v2 offset:54272
	ds_read_b64_tr_b16 v[10:11], v2 offset:54784
	v_mfma_f32_32x32x16_bf16 v[130:145], v[206:209], v[150:153], v[130:145]
	v_cvt_pk_bf16_f32 v162, v162, v163
	v_cvt_pk_bf16_f32 v163, v164, v165
	v_cvt_pk_bf16_f32 v164, v166, v167
	v_cvt_pk_bf16_f32 v165, v168, v169
	ds_read_b64_tr_b16 v[12:13], v2 offset:55296
	ds_read_b64_tr_b16 v[14:15], v2 offset:55808
	ds_read_b64_tr_b16 v[16:17], v2 offset:56320
	ds_read_b64_tr_b16 v[18:19], v2 offset:56832
	v_mfma_f32_32x32x16_bf16 v[114:129], v[210:213], v[154:157], v[114:129]
	v_exp_f32_e32 v170, v170
	v_exp_f32_e32 v171, v171
	v_exp_f32_e32 v172, v172
	v_add_f32_e32 v22, v22, v170
	v_exp_f32_e32 v173, v173
	s_cmp_gt_u32 s79, 8
	s_cbranch_scc1 .Lbd_dk_13
	s_add_i32 s0, s79, 3
	s_and_b32 s0, s0, 3
	s_lshl_b32 s0, s0, 13
	s_add_u32 m0, s24, s0
	s_cmp_gt_u32 s79, 7
	global_load_lds_dwordx4 v[26:27], off
	v_lshl_add_u64 v[26:27], v[26:27], 0, s[30:31]
	s_cbranch_scc1 .Lbd_dk_13
	s_and_b32 s0, s79, 3
	s_mulk_i32 s0, 0x3000
	s_add_u32 m0, s71, s0
	s_nop 0
	global_load_lds_dwordx4 v[24:25], off
	v_lshl_add_u64 v[24:25], v[24:25], 0, s[30:31]
.Lbd_dk_13:
	v_mfma_f32_32x32x16_bf16 v[130:145], v[214:217], v[154:157], v[130:145]
	v_add_f32_e32 v22, v22, v171
	v_exp_f32_e32 v174, v174
	v_add_f32_e32 v22, v22, v172
	v_exp_f32_e32 v175, v175
	v_add_f32_e32 v22, v22, v173
	v_mfma_f32_32x32x16_bf16 v[114:129], v[218:221], v[158:161], v[114:129]
	v_exp_f32_e32 v176, v176
	v_add_f32_e32 v22, v22, v174
	v_exp_f32_e32 v177, v177
	v_add_f32_e32 v22, v22, v175
	v_add_f32_e32 v22, v22, v176
	v_mfma_f32_32x32x16_bf16 v[130:145], v[222:225], v[158:161], v[130:145]
	v_add_f32_e32 v22, v22, v177
	v_cvt_pk_bf16_f32 v170, v170, v171
	v_cvt_pk_bf16_f32 v171, v172, v173
	v_cvt_pk_bf16_f32 v172, v174, v175
	v_cvt_pk_bf16_f32 v173, v176, v177
	s_waitcnt lgkmcnt(0)
	s_add_i32 s10, s79, 2
	s_and_b32 s10, s10, 3
	s_mulk_i32 s10, 0x3000
	v_add_u32_e32 v2, s10, v239
	v_mfma_f32_32x32x16_bf16 v[50:65], v[162:165], v[98:101], v[50:65]
	v_exp_f32_e32 v178, v178
	v_exp_f32_e32 v179, v179
	v_exp_f32_e32 v180, v180
	v_add_f32_e32 v22, v22, v178
	v_exp_f32_e32 v181, v181
	v_add_f32_e32 v22, v22, v179
	v_exp_f32_e32 v182, v182
	v_add_f32_e32 v22, v22, v180
	v_exp_f32_e32 v183, v183
	v_add_f32_e32 v22, v22, v181
	ds_read_b128 v[194:197], v2
	ds_read_b128 v[198:201], v2 offset:512
	v_mfma_f32_32x32x16_bf16 v[34:49], v[162:165], v[4:7], v[34:49]
	v_exp_f32_e32 v184, v184
	v_add_f32_e32 v22, v22, v182
	v_exp_f32_e32 v185, v185
	v_add_f32_e32 v22, v22, v183
	v_add_f32_e32 v22, v22, v184
	v_add_f32_e32 v22, v22, v185
	v_cvt_pk_bf16_f32 v178, v178, v179
	v_cvt_pk_bf16_f32 v179, v180, v181
	v_cvt_pk_bf16_f32 v180, v182, v183
	v_cvt_pk_bf16_f32 v181, v184, v185
	ds_read_b128 v[202:205], v2 offset:2048
	ds_read_b128 v[206:209], v2 offset:2560
	v_mfma_f32_32x32x16_bf16 v[50:65], v[170:173], v[102:105], v[50:65]
	v_exp_f32_e32 v186, v186
	v_exp_f32_e32 v187, v187
	v_exp_f32_e32 v188, v188
	v_add_f32_e32 v22, v22, v186
	v_exp_f32_e32 v189, v189
	v_add_f32_e32 v22, v22, v187
	v_exp_f32_e32 v190, v190
	v_add_f32_e32 v22, v22, v188
	v_exp_f32_e32 v191, v191
	v_add_f32_e32 v22, v22, v189
	ds_read_b128 v[210:213], v2 offset:4096
	ds_read_b128 v[214:217], v2 offset:4608
	v_mfma_f32_32x32x16_bf16 v[34:49], v[170:173], v[8:11], v[34:49]
	v_exp_f32_e32 v192, v192
	v_add_f32_e32 v22, v22, v190
	v_exp_f32_e32 v193, v193
	v_add_f32_e32 v22, v22, v191
	v_add_f32_e32 v22, v22, v192
	v_add_f32_e32 v22, v22, v193
	v_cvt_pk_bf16_f32 v186, v186, v187
	v_cvt_pk_bf16_f32 v187, v188, v189
	v_cvt_pk_bf16_f32 v188, v190, v191
	v_cvt_pk_bf16_f32 v189, v192, v193
	v_add_f32_e32 v240, v240, v22
	ds_read_b128 v[218:221], v2 offset:6144
	ds_read_b128 v[222:225], v2 offset:6656
	v_mfma_f32_32x32x16_bf16 v[50:65], v[178:181], v[106:109], v[50:65]
	v_max3_f32 v20, v114, v115, v116
	v_max3_f32 v21, v117, v118, v119
	v_max3_f32 v20, v20, v120, v121
	v_max3_f32 v21, v21, v122, v123
	v_max3_f32 v20, v20, v124, v125
	v_mfma_f32_32x32x16_bf16 v[34:49], v[178:181], v[12:15], v[34:49]
	v_max3_f32 v21, v21, v126, v127
	v_max3_f32 v20, v20, v128, v129
	v_max3_f32 v21, v21, v130, v131
	v_max3_f32 v20, v20, v132, v133
	v_max3_f32 v21, v21, v134, v135
	v_mfma_f32_32x32x16_bf16 v[50:65], v[186:189], v[110:113], v[50:65]
	v_max3_f32 v20, v20, v136, v137
	v_max3_f32 v21, v21, v138, v139
	v_max3_f32 v20, v20, v140, v141
	v_max3_f32 v21, v21, v142, v143
	v_mfma_f32_32x32x16_bf16 v[34:49], v[186:189], v[16:19], v[34:49]
	v_max3_f32 v20, v20, v144, v145
	v_max_f32_e32 v20, v20, v21
	v_cmp_lt_f32_e32 vcc, s41, v20
	s_cbranch_vccz .Lbd_nors_14
	s_nop 15
	s_nop 15
	v_mov_b32_e32 v21, v20
	s_nop 1
	v_permlane32_swap_b32_e32 v20, v21
	v_max_f32_e32 v20, v20, v21
	v_max_f32_e32 v20, v20, v20
	v_max_f32_e32 v170, 0, v20
	v_exp_f32_e64 v171, -v170
	v_add_f32_e32 v242, v242, v170
	v_xor_b32_e32 v82, 0x80000000, v242
	v_sub_f32_e32 v66, v23, v242
	v_mov_b32_e32 v83, v82
	v_mov_b32_e32 v67, v66
	v_mov_b32_e32 v84, v82
	v_mov_b32_e32 v68, v66
	v_mov_b32_e32 v85, v82
	v_mov_b32_e32 v69, v66
	v_mov_b32_e32 v86, v82
	v_mov_b32_e32 v70, v66
	v_mov_b32_e32 v87, v82
	v_mov_b32_e32 v71, v66
	v_mov_b32_e32 v88, v82
	v_mov_b32_e32 v72, v66
	v_mov_b32_e32 v89, v82
	v_mov_b32_e32 v73, v66
	v_mov_b32_e32 v90, v82
	v_mov_b32_e32 v74, v66
	v_mov_b32_e32 v91, v82
	v_mov_b32_e32 v75, v66
	v_mov_b32_e32 v92, v82
	v_mov_b32_e32 v76, v66
	v_mov_b32_e32 v93, v82
	v_mov_b32_e32 v77, v66
	v_mov_b32_e32 v94, v82
	v_mov_b32_e32 v78, v66
	v_mov_b32_e32 v95, v82
	v_mov_b32_e32 v79, v66
	v_mov_b32_e32 v96, v82
	v_mov_b32_e32 v80, v66
	v_mov_b32_e32 v97, v82
	v_mov_b32_e32 v81, v66
	v_sub_f32_e32 v114, v114, v170
	v_sub_f32_e32 v115, v115, v170
	v_sub_f32_e32 v116, v116, v170
	v_sub_f32_e32 v117, v117, v170
	v_sub_f32_e32 v118, v118, v170
	v_sub_f32_e32 v119, v119, v170
	v_sub_f32_e32 v120, v120, v170
	v_sub_f32_e32 v121, v121, v170
	v_sub_f32_e32 v122, v122, v170
	v_sub_f32_e32 v123, v123, v170
	v_sub_f32_e32 v124, v124, v170
	v_sub_f32_e32 v125, v125, v170
	v_sub_f32_e32 v126, v126, v170
	v_sub_f32_e32 v127, v127, v170
	v_sub_f32_e32 v128, v128, v170
	v_sub_f32_e32 v129, v129, v170
	v_sub_f32_e32 v130, v130, v170
	v_sub_f32_e32 v131, v131, v170
	v_sub_f32_e32 v132, v132, v170
	v_sub_f32_e32 v133, v133, v170
	v_sub_f32_e32 v134, v134, v170
	v_sub_f32_e32 v135, v135, v170
	v_sub_f32_e32 v136, v136, v170
	v_sub_f32_e32 v137, v137, v170
	v_sub_f32_e32 v138, v138, v170
	v_sub_f32_e32 v139, v139, v170
	v_sub_f32_e32 v140, v140, v170
	v_sub_f32_e32 v141, v141, v170
	v_sub_f32_e32 v142, v142, v170
	v_sub_f32_e32 v143, v143, v170
	v_sub_f32_e32 v144, v144, v170
	v_sub_f32_e32 v145, v145, v170
	v_mul_f32_e32 v240, v240, v171
	v_cmp_gt_u32_e32 vcc, 32, v233
	s_and_saveexec_b64 s[12:13], vcc
	ds_write_b32 v244, v171
	s_mov_b64 exec, s[12:13]
	ds_read_b128 v[174:177], v237 offset:0
	s_waitcnt lgkmcnt(0)
	v_mul_f32_e32 v50, v50, v174
	v_mul_f32_e32 v34, v34, v174
	v_mul_f32_e32 v51, v51, v175
	v_mul_f32_e32 v35, v35, v175
	v_mul_f32_e32 v52, v52, v176
	v_mul_f32_e32 v36, v36, v176
	v_mul_f32_e32 v53, v53, v177
	v_mul_f32_e32 v37, v37, v177
	ds_read_b128 v[174:177], v237 offset:32
	s_waitcnt lgkmcnt(0)
	v_mul_f32_e32 v54, v54, v174
	v_mul_f32_e32 v38, v38, v174
	v_mul_f32_e32 v55, v55, v175
	v_mul_f32_e32 v39, v39, v175
	v_mul_f32_e32 v56, v56, v176
	v_mul_f32_e32 v40, v40, v176
	v_mul_f32_e32 v57, v57, v177
	v_mul_f32_e32 v41, v41, v177
	ds_read_b128 v[174:177], v237 offset:64
	s_waitcnt lgkmcnt(0)
	v_mul_f32_e32 v58, v58, v174
	v_mul_f32_e32 v42, v42, v174
	v_mul_f32_e32 v59, v59, v175
	v_mul_f32_e32 v43, v43, v175
	v_mul_f32_e32 v60, v60, v176
	v_mul_f32_e32 v44, v44, v176
	v_mul_f32_e32 v61, v61, v177
	v_mul_f32_e32 v45, v45, v177
	ds_read_b128 v[174:177], v237 offset:96
	s_waitcnt lgkmcnt(0)
	v_mul_f32_e32 v62, v62, v174
	v_mul_f32_e32 v46, v46, v174
	v_mul_f32_e32 v63, v63, v175
	v_mul_f32_e32 v47, v47, v175
	v_mul_f32_e32 v64, v64, v176
	v_mul_f32_e32 v48, v48, v176
	v_mul_f32_e32 v65, v65, v177
	v_mul_f32_e32 v49, v49, v177

.Lbd_nors_26:
	ds_read2_b32 v[114:115], v29 offset0:187 offset1:186
	ds_read2_b32 v[116:117], v29 offset0:185 offset1:184
	ds_read2_b32 v[118:119], v29 offset0:179 offset1:178
	ds_read2_b32 v[120:121], v29 offset0:177 offset1:176
	ds_read2_b32 v[122:123], v29 offset0:171 offset1:170
	ds_read2_b32 v[124:125], v29 offset0:169 offset1:168
	ds_read2_b32 v[126:127], v29 offset0:163 offset1:162
	ds_read2_b32 v[128:129], v29 offset0:161 offset1:160
	ds_read2_b32 v[130:131], v29 offset0:155 offset1:154
	ds_read2_b32 v[132:133], v29 offset0:153 offset1:152
	ds_read2_b32 v[134:135], v29 offset0:147 offset1:146
	ds_read2_b32 v[136:137], v29 offset0:145 offset1:144
	ds_read2_b32 v[138:139], v29 offset0:139 offset1:138
	ds_read2_b32 v[140:141], v29 offset0:137 offset1:136
	ds_read2_b32 v[142:143], v29 offset0:131 offset1:130
	ds_read2_b32 v[144:145], v29 offset0:129 offset1:128
	s_add_i32 s79, s79, 1
	s_waitcnt vmcnt(2)
	s_cmp_lt_u32 s79, 9
	s_cbranch_scc1 .Lbd_w_27
	s_waitcnt vmcnt(0)
.Lbd_w_27:
	s_waitcnt lgkmcnt(0)
	s_barrier
	s_add_i32 s10, s79, 0
	s_and_b32 s10, s10, 3
	s_lshl_b32 s10, s10, 13
	v_add_u32_e32 v2, s10, v241
	v_sub_f32_e32 v114, v114, v242
	v_sub_f32_e32 v115, v115, v242
	v_sub_f32_e32 v116, v116, v242
	v_sub_f32_e32 v117, v117, v242
	v_sub_f32_e32 v118, v118, v242
	v_sub_f32_e32 v119, v119, v242
	v_sub_f32_e32 v120, v120, v242
	v_sub_f32_e32 v121, v121, v242
	v_sub_f32_e32 v122, v122, v242
	v_sub_f32_e32 v123, v123, v242
	v_sub_f32_e32 v124, v124, v242
	v_sub_f32_e32 v125, v125, v242
	v_sub_f32_e32 v126, v126, v242
	v_sub_f32_e32 v127, v127, v242
	v_sub_f32_e32 v128, v128, v242
	v_sub_f32_e32 v129, v129, v242
	v_sub_f32_e32 v130, v130, v242
	v_sub_f32_e32 v131, v131, v242
	v_mfma_f32_32x32x16_bf16 v[114:129], v[194:197], v[146:149], v[114:129]
	v_sub_f32_e32 v132, v132, v242
	v_sub_f32_e32 v133, v133, v242
	v_sub_f32_e32 v134, v134, v242
	v_sub_f32_e32 v135, v135, v242
	v_sub_f32_e32 v136, v136, v242
	v_sub_f32_e32 v137, v137, v242
	v_sub_f32_e32 v138, v138, v242
	v_sub_f32_e32 v139, v139, v242
	v_sub_f32_e32 v140, v140, v242
	v_sub_f32_e32 v141, v141, v242
	v_sub_f32_e32 v142, v142, v242
	v_sub_f32_e32 v143, v143, v242
	v_sub_f32_e32 v144, v144, v242
	v_sub_f32_e32 v145, v145, v242
	s_nop 1
	v_mfma_f32_32x32x16_bf16 v[130:145], v[198:201], v[146:149], v[130:145]
	v_exp_f32_e32 v162, v162
	v_exp_f32_e32 v163, v163
	v_exp_f32_e32 v164, v164
	v_add_f32_e32 v22, v162, v163
	v_exp_f32_e32 v165, v165
	ds_read_b64_tr_b16 v[98:99], v2 offset:49152
	ds_read_b64_tr_b16 v[100:101], v2 offset:49664
	ds_read_b64_tr_b16 v[102:103], v2 offset:50176
	ds_read_b64_tr_b16 v[104:105], v2 offset:50688
	v_exp_f32_e32 v166, v166
	v_add_f32_e32 v22, v22, v164
	v_exp_f32_e32 v167, v167
	v_add_f32_e32 v22, v22, v165
	v_exp_f32_e32 v168, v168
	ds_read_b64_tr_b16 v[106:107], v2 offset:51200
	ds_read_b64_tr_b16 v[108:109], v2 offset:51712
	ds_read_b64_tr_b16 v[110:111], v2 offset:52224
	ds_read_b64_tr_b16 v[112:113], v2 offset:52736
	v_mfma_f32_32x32x16_bf16 v[114:129], v[202:205], v[150:153], v[114:129]
	v_add_f32_e32 v22, v22, v166
	v_exp_f32_e32 v169, v169
	v_add_f32_e32 v22, v22, v167
	v_add_f32_e32 v22, v22, v168
	v_add_f32_e32 v22, v22, v169
	ds_read_b64_tr_b16 v[4:5], v2 offset:53248
	ds_read_b64_tr_b16 v[6:7], v2 offset:53760
	ds_read_b64_tr_b16 v[8:9], v2 offset:54272
	ds_read_b64_tr_b16 v[10:11], v2 offset:54784
	v_mfma_f32_32x32x16_bf16 v[130:145], v[206:209], v[150:153], v[130:145]
	v_cvt_pk_bf16_f32 v162, v162, v163
	v_cvt_pk_bf16_f32 v163, v164, v165
	v_cvt_pk_bf16_f32 v164, v166, v167
	v_cvt_pk_bf16_f32 v165, v168, v169
	ds_read_b64_tr_b16 v[12:13], v2 offset:55296
	ds_read_b64_tr_b16 v[14:15], v2 offset:55808
	ds_read_b64_tr_b16 v[16:17], v2 offset:56320
	ds_read_b64_tr_b16 v[18:19], v2 offset:56832
	v_mfma_f32_32x32x16_bf16 v[114:129], v[210:213], v[154:157], v[114:129]
	v_exp_f32_e32 v170, v170
	v_exp_f32_e32 v171, v171
	v_exp_f32_e32 v172, v172
	v_add_f32_e32 v22, v22, v170
	v_exp_f32_e32 v173, v173
	s_cmp_gt_u32 s79, 8
	s_cbranch_scc1 .Lbd_dk_29
	s_add_i32 s0, s79, 3
	s_and_b32 s0, s0, 3
	s_lshl_b32 s0, s0, 13
	s_add_u32 m0, s24, s0
	s_cmp_gt_u32 s79, 7
	global_load_lds_dwordx4 v[26:27], off
	v_lshl_add_u64 v[26:27], v[26:27], 0, s[30:31]
	s_cbranch_scc1 .Lbd_dk_29
	s_and_b32 s0, s79, 3
	s_mulk_i32 s0, 0x3000
	s_add_u32 m0, s71, s0
	s_nop 0
	global_load_lds_dwordx4 v[24:25], off
	v_lshl_add_u64 v[24:25], v[24:25], 0, s[30:31]

.Lbd_nors_30:
	ds_read2_b32 v[162:163], v29 offset0:123 offset1:122
	ds_read2_b32 v[164:165], v29 offset0:121 offset1:120
	ds_read2_b32 v[166:167], v29 offset0:115 offset1:114
	ds_read2_b32 v[168:169], v29 offset0:113 offset1:112
	ds_read2_b32 v[170:171], v29 offset0:107 offset1:106
	ds_read2_b32 v[172:173], v29 offset0:105 offset1:104
	ds_read2_b32 v[174:175], v29 offset0:99 offset1:98
	ds_read2_b32 v[176:177], v29 offset0:97 offset1:96
	ds_read2_b32 v[178:179], v29 offset0:91 offset1:90
	ds_read2_b32 v[180:181], v29 offset0:89 offset1:88
	ds_read2_b32 v[182:183], v29 offset0:83 offset1:82
	ds_read2_b32 v[184:185], v29 offset0:81 offset1:80
	ds_read2_b32 v[186:187], v29 offset0:75 offset1:74
	ds_read2_b32 v[188:189], v29 offset0:73 offset1:72
	ds_read2_b32 v[190:191], v29 offset0:67 offset1:66
	ds_read2_b32 v[192:193], v29 offset0:65 offset1:64
	s_add_i32 s79, s79, 1
	s_waitcnt vmcnt(2)
	s_cmp_lt_u32 s79, 9
	s_cbranch_scc1 .Lbd_w_31
	s_waitcnt vmcnt(0)
.Lbd_w_31:
	s_waitcnt lgkmcnt(0)
	s_barrier
	s_add_i32 s10, s79, 0
	s_and_b32 s10, s10, 3
	s_lshl_b32 s10, s10, 13
	v_add_u32_e32 v2, s10, v241
	v_sub_f32_e32 v162, v162, v242
	v_sub_f32_e32 v163, v163, v242
	v_sub_f32_e32 v164, v164, v242
	v_sub_f32_e32 v165, v165, v242
	v_sub_f32_e32 v166, v166, v242
	v_sub_f32_e32 v167, v167, v242
	v_sub_f32_e32 v168, v168, v242
	v_sub_f32_e32 v169, v169, v242
	v_sub_f32_e32 v170, v170, v242
	v_sub_f32_e32 v171, v171, v242
	v_sub_f32_e32 v172, v172, v242
	v_sub_f32_e32 v173, v173, v242
	v_sub_f32_e32 v174, v174, v242
	v_sub_f32_e32 v175, v175, v242
	v_sub_f32_e32 v176, v176, v242
	v_sub_f32_e32 v177, v177, v242
	v_sub_f32_e32 v178, v178, v242
	v_sub_f32_e32 v179, v179, v242
	v_mfma_f32_32x32x16_bf16 v[162:177], v[194:197], v[146:149], v[162:177]
	v_sub_f32_e32 v180, v180, v242
	v_sub_f32_e32 v181, v181, v242
	v_sub_f32_e32 v182, v182, v242
	v_sub_f32_e32 v183, v183, v242
	v_sub_f32_e32 v184, v184, v242
	v_sub_f32_e32 v185, v185, v242
	v_sub_f32_e32 v186, v186, v242
	v_sub_f32_e32 v187, v187, v242
	v_sub_f32_e32 v188, v188, v242
	v_sub_f32_e32 v189, v189, v242
	v_sub_f32_e32 v190, v190, v242
	v_sub_f32_e32 v191, v191, v242
	v_sub_f32_e32 v192, v192, v242
	v_sub_f32_e32 v193, v193, v242
	s_nop 1
	v_mfma_f32_32x32x16_bf16 v[178:193], v[198:201], v[146:149], v[178:193]
	v_exp_f32_e32 v114, v114
	v_exp_f32_e32 v115, v115
	v_exp_f32_e32 v116, v116
	v_add_f32_e32 v22, v114, v115
	v_exp_f32_e32 v117, v117
	ds_read_b64_tr_b16 v[98:99], v2 offset:49152
	ds_read_b64_tr_b16 v[100:101], v2 offset:49664
	ds_read_b64_tr_b16 v[102:103], v2 offset:50176
	ds_read_b64_tr_b16 v[104:105], v2 offset:50688
	v_exp_f32_e32 v118, v118
	v_add_f32_e32 v22, v22, v116
	v_exp_f32_e32 v119, v119
	v_add_f32_e32 v22, v22, v117
	v_exp_f32_e32 v120, v120
	ds_read_b64_tr_b16 v[106:107], v2 offset:51200
	ds_read_b64_tr_b16 v[108:109], v2 offset:51712
	ds_read_b64_tr_b16 v[110:111], v2 offset:52224
	ds_read_b64_tr_b16 v[112:113], v2 offset:52736
	v_mfma_f32_32x32x16_bf16 v[162:177], v[202:205], v[150:153], v[162:177]
	v_add_f32_e32 v22, v22, v118
	v_exp_f32_e32 v121, v121
	v_add_f32_e32 v22, v22, v119
	v_add_f32_e32 v22, v22, v120
	v_add_f32_e32 v22, v22, v121
	ds_read_b64_tr_b16 v[4:5], v2 offset:53248
	ds_read_b64_tr_b16 v[6:7], v2 offset:53760
	ds_read_b64_tr_b16 v[8:9], v2 offset:54272
	ds_read_b64_tr_b16 v[10:11], v2 offset:54784
	v_mfma_f32_32x32x16_bf16 v[178:193], v[206:209], v[150:153], v[178:193]
	v_cvt_pk_bf16_f32 v114, v114, v115
	v_cvt_pk_bf16_f32 v115, v116, v117
	v_cvt_pk_bf16_f32 v116, v118, v119
	v_cvt_pk_bf16_f32 v117, v120, v121
	ds_read_b64_tr_b16 v[12:13], v2 offset:55296
	ds_read_b64_tr_b16 v[14:15], v2 offset:55808
	ds_read_b64_tr_b16 v[16:17], v2 offset:56320
	ds_read_b64_tr_b16 v[18:19], v2 offset:56832
	v_mfma_f32_32x32x16_bf16 v[162:177], v[210:213], v[154:157], v[162:177]
	v_exp_f32_e32 v122, v122
	v_exp_f32_e32 v123, v123
	v_exp_f32_e32 v124, v124
	v_add_f32_e32 v22, v22, v122
	v_exp_f32_e32 v125, v125
	s_cmp_gt_u32 s79, 8
	s_cbranch_scc1 .Lbd_dk_33
	s_add_i32 s0, s79, 3
	s_and_b32 s0, s0, 3
	s_lshl_b32 s0, s0, 13
	s_add_u32 m0, s24, s0
	s_cmp_gt_u32 s79, 7
	global_load_lds_dwordx4 v[26:27], off
	v_lshl_add_u64 v[26:27], v[26:27], 0, s[30:31]
	s_cbranch_scc1 .Lbd_dk_33
	s_and_b32 s0, s79, 3
	s_mulk_i32 s0, 0x3000
	s_add_u32 m0, s71, s0
	s_nop 0
	global_load_lds_dwordx4 v[24:25], off
	v_lshl_add_u64 v[24:25], v[24:25], 0, s[30:31]

.Lbd_nors_34:
	ds_read2_b32 v[114:115], v29 offset0:59 offset1:58
	ds_read2_b32 v[116:117], v29 offset0:57 offset1:56
	ds_read2_b32 v[118:119], v29 offset0:51 offset1:50
	ds_read2_b32 v[120:121], v29 offset0:49 offset1:48
	ds_read2_b32 v[122:123], v29 offset0:43 offset1:42
	ds_read2_b32 v[124:125], v29 offset0:41 offset1:40
	ds_read2_b32 v[126:127], v29 offset0:35 offset1:34
	ds_read2_b32 v[128:129], v29 offset0:33 offset1:32
	ds_read2_b32 v[130:131], v29 offset0:27 offset1:26
	ds_read2_b32 v[132:133], v29 offset0:25 offset1:24
	ds_read2_b32 v[134:135], v29 offset0:19 offset1:18
	ds_read2_b32 v[136:137], v29 offset0:17 offset1:16
	ds_read2_b32 v[138:139], v29 offset0:11 offset1:10
	ds_read2_b32 v[140:141], v29 offset0:9 offset1:8
	ds_read2_b32 v[142:143], v29 offset0:3 offset1:2
	ds_read2_b32 v[144:145], v29 offset0:1 offset1:0
	s_add_i32 s79, s79, 1
	s_waitcnt vmcnt(2)
	s_cmp_lt_u32 s79, 9
	s_cbranch_scc1 .Lbd_w_35
	s_waitcnt vmcnt(0)

.Lbd_dk_37:
	v_mfma_f32_32x32x16_bf16 v[130:145], v[214:217], v[154:157], v[130:145]
	v_add_f32_e32 v22, v22, v171
	v_exp_f32_e32 v174, v174
	v_add_f32_e32 v22, v22, v172
	v_exp_f32_e32 v175, v175
	v_add_f32_e32 v22, v22, v173
	v_mfma_f32_32x32x16_bf16 v[114:129], v[218:221], v[158:161], v[114:129]
	v_exp_f32_e32 v176, v176
	v_add_f32_e32 v22, v22, v174
	v_exp_f32_e32 v177, v177
	v_add_f32_e32 v22, v22, v175
	v_add_f32_e32 v22, v22, v176
	v_mfma_f32_32x32x16_bf16 v[130:145], v[222:225], v[158:161], v[130:145]
	v_add_f32_e32 v22, v22, v177
	v_cvt_pk_bf16_f32 v170, v170, v171
	v_cvt_pk_bf16_f32 v171, v172, v173
	v_cvt_pk_bf16_f32 v172, v174, v175
	v_cvt_pk_bf16_f32 v173, v176, v177
	s_waitcnt lgkmcnt(0)
	v_mfma_f32_32x32x16_bf16 v[50:65], v[162:165], v[98:101], v[50:65]
	v_exp_f32_e32 v178, v178
	v_exp_f32_e32 v179, v179
	v_exp_f32_e32 v180, v180
	v_add_f32_e32 v22, v22, v178
	v_exp_f32_e32 v181, v181
	v_add_f32_e32 v22, v22, v179
	v_exp_f32_e32 v182, v182
	v_add_f32_e32 v22, v22, v180
	v_exp_f32_e32 v183, v183
	v_add_f32_e32 v22, v22, v181
	v_mfma_f32_32x32x16_bf16 v[34:49], v[162:165], v[4:7], v[34:49]
	v_exp_f32_e32 v184, v184
	v_add_f32_e32 v22, v22, v182
	v_exp_f32_e32 v185, v185
	v_add_f32_e32 v22, v22, v183
	v_add_f32_e32 v22, v22, v184
	v_add_f32_e32 v22, v22, v185
	v_cvt_pk_bf16_f32 v178, v178, v179
	v_cvt_pk_bf16_f32 v179, v180, v181
	v_cvt_pk_bf16_f32 v180, v182, v183
	v_cvt_pk_bf16_f32 v181, v184, v185
	v_mfma_f32_32x32x16_bf16 v[50:65], v[170:173], v[102:105], v[50:65]
	v_exp_f32_e32 v186, v186
	v_exp_f32_e32 v187, v187
	v_exp_f32_e32 v188, v188
	v_add_f32_e32 v22, v22, v186
	v_exp_f32_e32 v189, v189
	v_add_f32_e32 v22, v22, v187
	v_exp_f32_e32 v190, v190
	v_add_f32_e32 v22, v22, v188
	v_exp_f32_e32 v191, v191
	v_add_f32_e32 v22, v22, v189
	v_mfma_f32_32x32x16_bf16 v[34:49], v[170:173], v[8:11], v[34:49]
	v_exp_f32_e32 v192, v192
	v_add_f32_e32 v22, v22, v190
	v_exp_f32_e32 v193, v193
	v_add_f32_e32 v22, v22, v191
	v_add_f32_e32 v22, v22, v192
	v_add_f32_e32 v22, v22, v193
	v_cvt_pk_bf16_f32 v186, v186, v187
	v_cvt_pk_bf16_f32 v187, v188, v189
	v_cvt_pk_bf16_f32 v188, v190, v191
	v_cvt_pk_bf16_f32 v189, v192, v193
	v_add_f32_e32 v240, v240, v22
	v_mfma_f32_32x32x16_bf16 v[50:65], v[178:181], v[106:109], v[50:65]
	v_max3_f32 v20, v114, v115, v116
	v_max3_f32 v21, v117, v118, v119
	v_max3_f32 v20, v20, v120, v121
	v_max3_f32 v21, v21, v122, v123
	v_max3_f32 v20, v20, v124, v125
	v_mfma_f32_32x32x16_bf16 v[34:49], v[178:181], v[12:15], v[34:49]
	v_max3_f32 v21, v21, v126, v127
	v_max3_f32 v20, v20, v128, v129
	v_max3_f32 v21, v21, v130, v131
	v_max3_f32 v20, v20, v132, v133
	v_max3_f32 v21, v21, v134, v135
	v_mfma_f32_32x32x16_bf16 v[50:65], v[186:189], v[110:113], v[50:65]
	v_max3_f32 v20, v20, v136, v137
	v_max3_f32 v21, v21, v138, v139
	v_max3_f32 v20, v20, v140, v141
	v_max3_f32 v21, v21, v142, v143
	v_mfma_f32_32x32x16_bf16 v[34:49], v[186:189], v[16:19], v[34:49]
	v_max3_f32 v20, v20, v144, v145
	v_max_f32_e32 v20, v20, v21
	v_cmp_lt_f32_e32 vcc, s41, v20
	s_cbranch_vccz .Lbd_nors_38
	s_nop 15
	s_nop 15
	v_mov_b32_e32 v21, v20
	s_nop 1
	v_permlane32_swap_b32_e32 v20, v21
	v_max_f32_e32 v20, v20, v21
	v_max_f32_e32 v20, v20, v20
	v_max_f32_e32 v170, 0, v20
	v_exp_f32_e64 v171, -v170
	v_add_f32_e32 v242, v242, v170
	v_xor_b32_e32 v82, 0x80000000, v242
	v_sub_f32_e32 v66, v23, v242
	v_mov_b32_e32 v83, v82
	v_mov_b32_e32 v67, v66
	v_mov_b32_e32 v84, v82
	v_mov_b32_e32 v68, v66
	v_mov_b32_e32 v85, v82
	v_mov_b32_e32 v69, v66
	v_mov_b32_e32 v86, v82
	v_mov_b32_e32 v70, v66
	v_mov_b32_e32 v87, v82
	v_mov_b32_e32 v71, v66
	v_mov_b32_e32 v88, v82
	v_mov_b32_e32 v72, v66
	v_mov_b32_e32 v89, v82
	v_mov_b32_e32 v73, v66
	v_mov_b32_e32 v90, v82
	v_mov_b32_e32 v74, v66
	v_mov_b32_e32 v91, v82
	v_mov_b32_e32 v75, v66
	v_mov_b32_e32 v92, v82
	v_mov_b32_e32 v76, v66
	v_mov_b32_e32 v93, v82
	v_mov_b32_e32 v77, v66
	v_mov_b32_e32 v94, v82
	v_mov_b32_e32 v78, v66
	v_mov_b32_e32 v95, v82
	v_mov_b32_e32 v79, v66
	v_mov_b32_e32 v96, v82
	v_mov_b32_e32 v80, v66
	v_mov_b32_e32 v97, v82
	v_mov_b32_e32 v81, v66
	v_sub_f32_e32 v114, v114, v170
	v_sub_f32_e32 v115, v115, v170
	v_sub_f32_e32 v116, v116, v170
	v_sub_f32_e32 v117, v117, v170
	v_sub_f32_e32 v118, v118, v170
	v_sub_f32_e32 v119, v119, v170
	v_sub_f32_e32 v120, v120, v170
	v_sub_f32_e32 v121, v121, v170
	v_sub_f32_e32 v122, v122, v170
	v_sub_f32_e32 v123, v123, v170
	v_sub_f32_e32 v124, v124, v170
	v_sub_f32_e32 v125, v125, v170
	v_sub_f32_e32 v126, v126, v170
	v_sub_f32_e32 v127, v127, v170
	v_sub_f32_e32 v128, v128, v170
	v_sub_f32_e32 v129, v129, v170
	v_sub_f32_e32 v130, v130, v170
	v_sub_f32_e32 v131, v131, v170
	v_sub_f32_e32 v132, v132, v170
	v_sub_f32_e32 v133, v133, v170
	v_sub_f32_e32 v134, v134, v170
	v_sub_f32_e32 v135, v135, v170
	v_sub_f32_e32 v136, v136, v170
	v_sub_f32_e32 v137, v137, v170
	v_sub_f32_e32 v138, v138, v170
	v_sub_f32_e32 v139, v139, v170
	v_sub_f32_e32 v140, v140, v170
	v_sub_f32_e32 v141, v141, v170
	v_sub_f32_e32 v142, v142, v170
	v_sub_f32_e32 v143, v143, v170
	v_sub_f32_e32 v144, v144, v170
	v_sub_f32_e32 v145, v145, v170
	v_mul_f32_e32 v240, v240, v171
	v_cmp_gt_u32_e32 vcc, 32, v233
	s_and_saveexec_b64 s[12:13], vcc
	ds_write_b32 v244, v171
	s_mov_b64 exec, s[12:13]
	ds_read_b128 v[174:177], v237 offset:0
	s_waitcnt lgkmcnt(0)
	v_mul_f32_e32 v50, v50, v174
	v_mul_f32_e32 v34, v34, v174
	v_mul_f32_e32 v51, v51, v175
	v_mul_f32_e32 v35, v35, v175
	v_mul_f32_e32 v52, v52, v176
	v_mul_f32_e32 v36, v36, v176
	v_mul_f32_e32 v53, v53, v177
	v_mul_f32_e32 v37, v37, v177
	ds_read_b128 v[174:177], v237 offset:32
	s_waitcnt lgkmcnt(0)
	v_mul_f32_e32 v54, v54, v174
	v_mul_f32_e32 v38, v38, v174
	v_mul_f32_e32 v55, v55, v175
	v_mul_f32_e32 v39, v39, v175
	v_mul_f32_e32 v56, v56, v176
	v_mul_f32_e32 v40, v40, v176
	v_mul_f32_e32 v57, v57, v177
	v_mul_f32_e32 v41, v41, v177
	ds_read_b128 v[174:177], v237 offset:64
	s_waitcnt lgkmcnt(0)
	v_mul_f32_e32 v58, v58, v174
	v_mul_f32_e32 v42, v42, v174
	v_mul_f32_e32 v59, v59, v175
	v_mul_f32_e32 v43, v43, v175
	v_mul_f32_e32 v60, v60, v176
	v_mul_f32_e32 v44, v44, v176
	v_mul_f32_e32 v61, v61, v177
	v_mul_f32_e32 v45, v45, v177
	ds_read_b128 v[174:177], v237 offset:96
	s_waitcnt lgkmcnt(0)
	v_mul_f32_e32 v62, v62, v174
	v_mul_f32_e32 v46, v46, v174
	v_mul_f32_e32 v63, v63, v175
	v_mul_f32_e32 v47, v47, v175
	v_mul_f32_e32 v64, v64, v176
	v_mul_f32_e32 v48, v48, v176
	v_mul_f32_e32 v65, v65, v177
	v_mul_f32_e32 v49, v49, v177
